# v41 + barrier-time prefetch of WGU limited to its last quarter (the tiles the reversed up order uses first)
# speedup vs baseline: 1.0021x; 1.0021x over previous
.LBB0_266:
	v_readlane_b32 s10, v254, 17
	s_and_b32 s0, s10, 1
	s_cmp_eq_u32 s0, 0
	s_cselect_b64 s[4:5], -1, 0
	s_cmp_eq_u32 s0, 1
	s_cselect_b64 s[2:3], -1, 0
	s_and_b64 vcc, exec, s[2:3]
	v_readlane_b32 s11, v254, 18
	s_cbranch_vccz .LBB0_283
	s_add_i32 s2, s66, 2
	s_cmp_lt_i32 s2, s91
	s_cselect_b64 s[6:7], -1, 0
	s_and_b64 s[6:7], s[8:9], s[6:7]
	s_cmp_lg_u32 s10, 7
	s_cbranch_scc0 .LBB0_284
	s_mov_b64 s[10:11], 0
	s_and_b64 vcc, exec, s[6:7]
	s_mov_b64 s[12:13], 0
	s_cbranch_vccz .LBB0_285
	s_waitcnt vmcnt(0)
	v_mov_b32_e32 v1, v0
	s_waitcnt vmcnt(0) lgkmcnt(0)
	s_barrier
	s_nop 0
	v_readfirstlane_b32 s3, v1
	s_cmp_lt_u32 s3, 64
	s_cbranch_scc1 .LBB0_273
	s_lshr_b32 s0, s3, 6
	s_add_i32 s0, s93, s0
	s_lshl_b32 s80, s0, 10
	s_add_i32 s80, s80, 0x2100000
	s_cmp_gt_u32 s80, 0x2bfffff
	s_cbranch_scc1 .LBB0_273
	v_readlane_b32 s0, v254, 17
	s_mul_i32 s0, s0, 0x2c00000
	s_add_u32 s12, s86, s0
	v_lshlrev_b32_e32 v1, 4, v1
	v_readlane_b32 s1, v254, 18
	s_addc_u32 s13, s87, 0
	v_and_b32_e32 v186, 0x3f0, v1
	v_lshl_add_u64 v[2:3], s[12:13], 0, v[186:187]
	s_mov_b64 s[0:1], 0x2e00000
	v_lshl_add_u64 v[2:3], v[2:3], 0, s[0:1]

.LBB0_1149:
	s_add_i32 s66, s66, 8
	s_cmp_lt_i32 s66, s91
	s_cselect_b64 s[0:1], -1, 0
	s_and_b64 s[0:1], s[6:7], s[0:1]
	s_andn2_b64 vcc, exec, s[0:1]
	s_cbranch_vccnz .LBB0_1202
	s_waitcnt vmcnt(0)
	v_mov_b32_e32 v1, v0
	s_waitcnt vmcnt(0) lgkmcnt(0)
	s_barrier
	s_nop 0
	v_readfirstlane_b32 s2, v1
	s_cmp_lt_u32 s2, 64
	s_cbranch_scc1 .LBB0_1154
	s_lshr_b32 s0, s2, 6
	s_add_i32 s0, s93, s0
	s_lshl_b32 s80, s0, 10
	s_add_i32 s80, s80, 0x2100000
	s_cmp_gt_u32 s80, 0x2bfffff
	s_cbranch_scc1 .LBB0_1154
	v_readlane_b32 s0, v254, 17
	s_mul_i32 s0, s0, 0x2c00000
	v_readlane_b32 s1, v254, 18
	s_add_u32 s0, s86, s0
	v_lshlrev_b32_e32 v1, 4, v1
	s_addc_u32 s1, s87, 0
	v_and_b32_e32 v186, 0x3f0, v1
	v_lshl_add_u64 v[2:3], s[0:1], 0, v[186:187]
	s_mov_b64 s[0:1], 0x2e00000
	v_lshl_add_u64 v[2:3], v[2:3], 0, s[0:1]
